# k5 plus layer-0 norm row loop with a 2-deep row prefetch (two row pairs in flight per workgroup) and hoisted g / early scale-shift loads
# speedup vs baseline: 1.0055x; 1.0055x over previous
.LBB0_593:
	s_cmp_lt_i32 s96, 3
	s_cselect_b64 s[0:1], -1, 0
	s_and_b64 s[4:5], s[0:1], s[4:5]
	s_andn2_b64 vcc, exec, s[4:5]
	s_cbranch_vccnz .LBB0_603
	s_add_i32 s3, 0, 0x25490
	v_mov_b32_e32 v1, s3
	s_waitcnt vmcnt(0)
	ds_read_b64 v[2:3], v1
	s_add_i32 s4, 0, 0x254a0
	s_add_i32 s5, 0, 0x254c0
	s_add_i32 s6, 0, 0x25588
	s_add_i32 s7, 0, 0x25628
	v_mov_b32_e32 v1, s4
	v_mov_b32_e32 v6, s5
	v_mov_b32_e32 v8, s6
	ds_read_b64 v[4:5], v1
	ds_read_b64 v[6:7], v6
	ds_read_b64 v[8:9], v8
	v_mov_b32_e32 v1, s7
	s_waitcnt lgkmcnt(3)
	v_readfirstlane_b32 s3, v3
	v_readfirstlane_b32 s10, v2
	ds_read_b64 v[2:3], v1
	s_cmpk_gt_i32 s2, 0x10ff
	s_waitcnt lgkmcnt(3)
	v_readfirstlane_b32 s11, v5
	v_readfirstlane_b32 s16, v4
	s_waitcnt lgkmcnt(2)
	v_readfirstlane_b32 s9, v7
	v_readfirstlane_b32 s8, v6
	s_waitcnt lgkmcnt(1)
	v_readfirstlane_b32 s5, v9
	v_readfirstlane_b32 s4, v8
	s_waitcnt lgkmcnt(0)
	v_readfirstlane_b32 s7, v3
	v_readfirstlane_b32 s6, v2
	v_mov_b32_e32 v2, v0
	s_cbranch_scc1 .LBB0_603
	v_ashrrev_i32_e32 v1, 8, v2
	s_lshl_b32 s17, s2, 1
	v_add_u32_e32 v3, s17, v1
	s_movk_i32 s18, 0x2000
	v_add_u32_e32 v4, 0xffffe000, v3
	v_cmp_gt_i32_e32 vcc, s18, v3
	v_ashrrev_i32_e32 v5, 31, v3
	v_mov_b32_e32 v6, s3
	v_cndmask_b32_e32 v4, v4, v3, vcc
	v_mov_b32_e32 v3, s11
	v_cndmask_b32_e32 v5, 0, v5, vcc
	v_cndmask_b32_e32 v7, v3, v6, vcc
	v_mov_b32_e32 v3, s16
	v_mov_b32_e32 v6, s10
	v_lshlrev_b32_e32 v2, 2, v2
	v_cndmask_b32_e32 v6, v3, v6, vcc
	v_lshlrev_b64 v[4:5], 14, v[4:5]
	v_and_b32_e32 v36, 0x3fc, v2
	v_mov_b32_e32 v35, 0
	v_lshl_add_u64 v[4:5], v[6:7], 0, v[4:5]
	v_lshlrev_b32_e32 v34, 2, v36
	v_lshl_add_u64 v[14:15], v[4:5], 0, v[34:35]
	v_add_co_u32_e32 v2, vcc, s18, v14
	s_movk_i32 s19, 0x3000
	s_nop 0
	v_addc_co_u32_e32 v3, vcc, 0, v15, vcc
	v_add_co_u32_e32 v16, vcc, s19, v14
	global_load_dwordx4 v[10:13], v[2:3], off offset:-4096
	global_load_dwordx4 v[6:9], v[2:3], off
	v_addc_co_u32_e32 v17, vcc, 0, v15, vcc
	global_load_dwordx4 v[18:21], v[14:15], off
	global_load_dwordx4 v[2:5], v[16:17], off
	v_mbcnt_lo_u32_b32 v14, -1, 0
	v_mbcnt_hi_u32_b32 v14, -1, v14
	v_and_b32_e32 v15, 64, v14
	v_add_u32_e32 v15, 64, v15
	v_xor_b32_e32 v16, 32, v14
	v_cmp_lt_i32_e32 vcc, v16, v15
	v_lshl_add_u64 v[38:39], s[8:9], 0, v[34:35]
	v_or_b32_e32 v40, 0x800, v36
	v_cndmask_b32_e32 v16, v14, v16, vcc
	v_lshlrev_b32_e32 v37, 2, v16
	v_xor_b32_e32 v16, 16, v14
	v_cmp_lt_i32_e32 vcc, v16, v15
	v_or_b32_e32 v42, 0xc00, v36
	s_lshl_b32 s21, s24, 1
	v_cndmask_b32_e32 v16, v14, v16, vcc
	v_lshlrev_b32_e32 v41, 2, v16
	v_xor_b32_e32 v16, 8, v14
	v_cmp_lt_i32_e32 vcc, v16, v15
	v_mov_b32_e32 v59, 0x358637bd
	s_mov_b32 s22, 0x800000
	v_cndmask_b32_e32 v16, v14, v16, vcc
	v_lshlrev_b32_e32 v43, 2, v16
	v_xor_b32_e32 v16, 4, v14
	v_cmp_lt_i32_e32 vcc, v16, v15
	s_movk_i32 s23, 0x7fff
	s_mov_b32 s25, 0xffff0000
	v_cndmask_b32_e32 v16, v14, v16, vcc
	v_lshlrev_b32_e32 v56, 2, v16
	v_xor_b32_e32 v16, 2, v14
	v_cmp_lt_i32_e32 vcc, v16, v15
	s_mov_b32 s26, s2
	s_nop 0
	v_cndmask_b32_e32 v16, v14, v16, vcc
	v_lshlrev_b32_e32 v57, 2, v16
	v_xor_b32_e32 v16, 1, v14
	v_cmp_lt_i32_e32 vcc, v16, v15
	s_nop 1
	v_cndmask_b32_e32 v14, v14, v16, vcc
	v_lshlrev_b32_e32 v58, 2, v14
	v_or_b32_e32 v14, 0x400, v36
	v_lshlrev_b32_e32 v34, 2, v14
	v_lshl_add_u64 v[44:45], s[8:9], 0, v[34:35]
	v_lshlrev_b32_e32 v34, 2, v40
	v_lshl_add_u64 v[46:47], s[8:9], 0, v[34:35]
	v_lshlrev_b32_e32 v34, 2, v42
	v_lshl_add_u64 v[48:49], s[8:9], 0, v[34:35]
	s_add_i32 s8, s2, s24
	s_lshl_b32 s20, s8, 1
	s_mov_b64 s[8:9], 0x4000
	v_lshlrev_b32_e32 v50, 2, v14
	s_mov_b64 s[66:67], 0x1000
	s_mov_b64 s[68:69], 0x3000
	global_load_dwordx4 v[104:107], v[38:39], off
	global_load_dwordx4 v[108:111], v[44:45], off
	global_load_dwordx4 v[112:115], v[46:47], off
	global_load_dwordx4 v[116:119], v[48:49], off
	s_mov_b32 s60, 0
	s_add_i32 s64, s20, s21
	v_lshlrev_b32_e32 v34, 2, v36
	s_add_i32 s65, s2, s24
	s_cmpk_gt_i32 s65, 0x10ff
	s_cbranch_scc1 .Ln0_pre_noitem1
	v_add_u32_e32 v188, s20, v1
	v_add_u32_e32 v190, 0xffffe000, v188
	v_cmp_gt_i32_e32 vcc, s18, v188
	v_ashrrev_i32_e32 v189, 31, v188
	v_mov_b32_e32 v191, s3
	v_cndmask_b32_e32 v188, v190, v188, vcc
	v_mov_b32_e32 v190, s11
	v_cndmask_b32_e32 v189, 0, v189, vcc
	v_cndmask_b32_e32 v191, v190, v191, vcc
	v_mov_b32_e32 v190, s16
	v_mov_b32_e32 v192, s10
	v_cndmask_b32_e32 v190, v190, v192, vcc
	v_lshlrev_b64 v[188:189], 14, v[188:189]
	v_lshl_add_u64 v[188:189], v[190:191], 0, v[188:189]
	v_lshl_add_u64 v[194:195], v[188:189], 0, v[34:35]
	v_add_co_u32_e32 v188, vcc, s18, v194
	s_nop 1
	v_addc_co_u32_e32 v189, vcc, 0, v195, vcc
	v_add_co_u32_e32 v196, vcc, s19, v194
	global_load_dwordx4 v[22:25], v[188:189], off offset:-4096
	global_load_dwordx4 v[26:29], v[188:189], off
	v_addc_co_u32_e32 v197, vcc, 0, v195, vcc
	global_load_dwordx4 v[30:33], v[194:195], off
	global_load_dwordx4 v[14:17], v[196:197], off
	s_waitcnt vmcnt(8)
	s_branch .LBB0_597
.Ln0_pre_noitem1:
	s_waitcnt vmcnt(4)
	s_branch .LBB0_597
.LBB0_596:
	s_or_b64 exec, exec, s[14:15]
	s_waitcnt lgkmcnt(0)
	s_barrier
	s_waitcnt lgkmcnt(0)
	v_ashrrev_i32_e32 v34, 6, v51
	v_lshlrev_b32_e32 v34, 2, v34
	v_and_b32_e32 v51, -16, v34
	v_add_u32_e32 v51, 0, v51
	ds_read_b96 v[72:74], v51
	v_or_b32_e32 v34, 12, v34
	v_add_u32_e32 v34, 0, v34
	v_lshlrev_b64 v[54:55], 13, v[54:55]
	v_mov_b32_e32 v51, v35
	s_waitcnt lgkmcnt(0)
	v_mov_b32_e32 v78, v73
	ds_read_b32 v73, v34
	v_mov_b32_e32 v79, v74
	v_add_u32_e32 v1, s21, v1
	s_waitcnt lgkmcnt(0)
	v_pk_add_f32 v[72:73], v[78:79], v[72:73]
	s_nop 0
	v_add_f32_e32 v34, v72, v73
	v_fmamk_f32 v34, v34, 0x39800000, v59
	v_mul_f32_e32 v72, 0x4b800000, v34
	v_cmp_gt_f32_e32 vcc, s22, v34
	s_nop 1
	v_cndmask_b32_e32 v34, v34, v72, vcc
	v_rsq_f32_e32 v74, v34
	v_lshl_add_u64 v[72:73], s[4:5], 0, v[54:55]
	v_lshlrev_b32_e32 v34, 1, v36
	v_lshl_add_u64 v[54:55], v[72:73], 0, v[34:35]
	v_mul_f32_e32 v34, 0x45800000, v74
	v_cndmask_b32_e32 v74, v74, v34, vcc
	v_pk_mul_f32 v[20:21], v[20:21], v[74:75] op_sel_hi:[1,0]
	v_pk_mul_f32 v[18:19], v[18:19], v[74:75] op_sel_hi:[1,0]
	v_pk_mul_f32 v[12:13], v[12:13], v[74:75] op_sel_hi:[1,0]
	v_pk_mul_f32 v[10:11], v[10:11], v[74:75] op_sel_hi:[1,0]
	v_pk_mul_f32 v[8:9], v[8:9], v[74:75] op_sel_hi:[1,0]
	v_pk_mul_f32 v[6:7], v[6:7], v[74:75] op_sel_hi:[1,0]
	v_pk_mul_f32 v[70:71], v[4:5], v[74:75] op_sel_hi:[1,0]
	v_pk_mul_f32 v[76:77], v[2:3], v[74:75] op_sel_hi:[1,0]
	s_waitcnt vmcnt(4)
	s_cmp_lg_u64 s[62:63], 0
	s_cbranch_scc0 .Ln0_vec_ready
	s_waitcnt vmcnt(0)
.Ln0_vec_ready:
	v_pk_mul_f32 v[18:19], v[104:105], v[18:19]
	v_pk_mul_f32 v[20:21], v[106:107], v[20:21]
	v_pk_add_f32 v[60:61], v[122:123], 1.0 op_sel_hi:[1,0]
	v_pk_add_f32 v[62:63], v[120:121], 1.0 op_sel_hi:[1,0]
	v_pk_fma_f32 v[20:21], v[60:61], v[20:21], v[138:139]
	v_pk_fma_f32 v[18:19], v[62:63], v[18:19], v[136:137]
	v_cvt_pk_bf16_f32 v18, v18, v19
	v_cvt_pk_bf16_f32 v19, v20, v21
	global_store_dwordx2 v[54:55], v[18:19], off
	v_pk_mul_f32 v[10:11], v[108:109], v[10:11]
	v_pk_mul_f32 v[12:13], v[110:111], v[12:13]
	v_pk_add_f32 v[60:61], v[126:127], 1.0 op_sel_hi:[1,0]
	v_pk_add_f32 v[62:63], v[124:125], 1.0 op_sel_hi:[1,0]
	v_pk_fma_f32 v[12:13], v[60:61], v[12:13], v[142:143]
	v_pk_fma_f32 v[10:11], v[62:63], v[10:11], v[140:141]
	v_cvt_pk_bf16_f32 v10, v10, v11
	v_cvt_pk_bf16_f32 v11, v12, v13
	global_store_dwordx2 v[54:55], v[10:11], off offset:2048
	v_lshlrev_b32_e32 v34, 1, v40
	v_lshl_add_u64 v[54:55], v[72:73], 0, v[34:35]
	v_pk_mul_f32 v[6:7], v[112:113], v[6:7]
	v_pk_mul_f32 v[8:9], v[114:115], v[8:9]
	v_pk_add_f32 v[60:61], v[130:131], 1.0 op_sel_hi:[1,0]
	v_pk_add_f32 v[62:63], v[128:129], 1.0 op_sel_hi:[1,0]
	v_pk_fma_f32 v[8:9], v[60:61], v[8:9], v[146:147]
	v_pk_fma_f32 v[6:7], v[62:63], v[6:7], v[144:145]
	v_cvt_pk_bf16_f32 v6, v6, v7
	v_cvt_pk_bf16_f32 v7, v8, v9
	global_store_dwordx2 v[54:55], v[6:7], off
	v_lshlrev_b32_e32 v34, 1, v42
	v_lshl_add_u64 v[68:69], v[72:73], 0, v[34:35]
	v_pk_mul_f32 v[164:165], v[76:77], v[116:117]
	v_pk_mul_f32 v[166:167], v[70:71], v[118:119]
	v_pk_add_f32 v[60:61], v[134:135], 1.0 op_sel_hi:[1,0]
	v_pk_add_f32 v[62:63], v[132:133], 1.0 op_sel_hi:[1,0]
	v_pk_fma_f32 v[166:167], v[166:167], v[60:61], v[150:151]
	v_pk_fma_f32 v[164:165], v[164:165], v[62:63], v[148:149]
	v_cvt_pk_bf16_f32 v164, v164, v165
	v_cvt_pk_bf16_f32 v165, v166, v167
	global_store_dwordx2 v[68:69], v[164:165], off
	s_cmp_lg_u64 s[12:13], 0
	s_cbranch_scc1 .LBB0_603
	s_waitcnt vmcnt(8)
	s_cmp_eq_u32 s60, 0
	s_cbranch_scc0 .Ln0_cp_odd
	v_mov_b32_e32 v10, v22
	v_mov_b32_e32 v11, v23
	v_mov_b32_e32 v12, v24
	v_mov_b32_e32 v13, v25
	v_mov_b32_e32 v6, v26
	v_mov_b32_e32 v7, v27
	v_mov_b32_e32 v8, v28
	v_mov_b32_e32 v9, v29
	v_mov_b32_e32 v18, v30
	v_mov_b32_e32 v19, v31
	v_mov_b32_e32 v20, v32
	v_mov_b32_e32 v21, v33
	v_mov_b32_e32 v2, v14
	v_mov_b32_e32 v3, v15
	v_mov_b32_e32 v4, v16
	v_mov_b32_e32 v5, v17
	s_branch .Ln0_cp_done
.Ln0_cp_odd:
	v_mov_b32_e32 v10, v172
	v_mov_b32_e32 v11, v173
	v_mov_b32_e32 v12, v174
	v_mov_b32_e32 v13, v175
	v_mov_b32_e32 v6, v176
	v_mov_b32_e32 v7, v177
	v_mov_b32_e32 v8, v178
	v_mov_b32_e32 v9, v179
	v_mov_b32_e32 v18, v180
	v_mov_b32_e32 v19, v181
	v_mov_b32_e32 v20, v182
	v_mov_b32_e32 v21, v183
	v_mov_b32_e32 v2, v184
	v_mov_b32_e32 v3, v185
	v_mov_b32_e32 v4, v186
	v_mov_b32_e32 v5, v187
.Ln0_cp_done:
	s_xor_b32 s60, s60, 1
.LBB0_597:
	v_add_u32_e32 v54, s17, v1
	v_cmp_gt_i32_e32 vcc, s18, v54
	v_mov_b64_e32 v[52:53], 0x6000
	v_ashrrev_i32_e32 v55, 31, v54
	s_and_saveexec_b64 s[12:13], vcc
	v_lshrrev_b32_e32 v198, 20, v55
	v_add_u32_e32 v198, v54, v198
	v_ashrrev_i32_e32 v198, 12, v198
	v_mul_i32_i24_e32 v52, 0x3000, v198
	v_ashrrev_i32_e32 v53, 31, v52
	s_or_b64 exec, exec, s[12:13]
	s_add_i32 s26, s26, s24
	s_cmpk_gt_i32 s26, 0x10ff
	s_cselect_b64 s[12:13], -1, 0
	s_and_b64 vcc, exec, s[12:13]
	v_lshlrev_b32_e32 v34, 2, v36
	v_lshl_add_u64 v[152:153], v[52:53], 2, s[6:7]
	v_lshl_add_u64 v[152:153], v[152:153], 0, v[34:35]
	v_lshl_add_u64 v[154:155], v[152:153], 0, s[8:9]
	v_lshl_add_u64 v[156:157], v[152:153], 0, s[66:67]
	v_lshl_add_u64 v[158:159], v[152:153], 0, s[68:69]
	v_lshl_add_u64 v[160:161], v[154:155], 0, s[66:67]
	v_lshl_add_u64 v[162:163], v[154:155], 0, s[68:69]
	global_load_dwordx4 v[120:123], v[160:161], off offset:-4096
	global_load_dwordx4 v[124:127], v[160:161], off
	global_load_dwordx4 v[128:131], v[162:163], off offset:-4096
	global_load_dwordx4 v[132:135], v[162:163], off
	global_load_dwordx4 v[136:139], v[156:157], off offset:-4096
	global_load_dwordx4 v[140:143], v[156:157], off
	global_load_dwordx4 v[144:147], v[158:159], off offset:-4096
	global_load_dwordx4 v[148:151], v[158:159], off
	s_add_i32 s65, s26, s24
	s_cmpk_gt_i32 s65, 0x10ff
	s_cselect_b64 s[62:63], -1, 0
	s_cbranch_scc1 .LBB0_601
	s_cmp_eq_u32 s60, 0
	s_cbranch_scc0 .Ln0_ld_odd
	v_add_u32_e32 v188, s64, v1
	v_add_u32_e32 v190, 0xffffe000, v188
	v_cmp_gt_i32_e32 vcc, s18, v188
	v_ashrrev_i32_e32 v189, 31, v188
	v_mov_b32_e32 v191, s3
	v_cndmask_b32_e32 v188, v190, v188, vcc
	v_mov_b32_e32 v190, s11
	v_cndmask_b32_e32 v189, 0, v189, vcc
	v_cndmask_b32_e32 v191, v190, v191, vcc
	v_mov_b32_e32 v190, s16
	v_mov_b32_e32 v192, s10
	v_cndmask_b32_e32 v190, v190, v192, vcc
	v_lshlrev_b64 v[188:189], 14, v[188:189]
	v_lshl_add_u64 v[188:189], v[190:191], 0, v[188:189]
	v_lshl_add_u64 v[194:195], v[188:189], 0, v[34:35]
	v_add_co_u32_e32 v188, vcc, s18, v194
	s_nop 1
	v_addc_co_u32_e32 v189, vcc, 0, v195, vcc
	v_add_co_u32_e32 v196, vcc, s19, v194
	global_load_dwordx4 v[172:175], v[188:189], off offset:-4096
	global_load_dwordx4 v[176:179], v[188:189], off
	v_addc_co_u32_e32 v197, vcc, 0, v195, vcc
	global_load_dwordx4 v[180:183], v[194:195], off
	global_load_dwordx4 v[184:187], v[196:197], off
	s_branch .LBB0_601
.Ln0_ld_odd:
	v_add_u32_e32 v188, s64, v1
	v_add_u32_e32 v190, 0xffffe000, v188
	v_cmp_gt_i32_e32 vcc, s18, v188
	v_ashrrev_i32_e32 v189, 31, v188
	v_mov_b32_e32 v191, s3
	v_cndmask_b32_e32 v188, v190, v188, vcc
	v_mov_b32_e32 v190, s11
	v_cndmask_b32_e32 v189, 0, v189, vcc
	v_cndmask_b32_e32 v191, v190, v191, vcc
	v_mov_b32_e32 v190, s16
	v_mov_b32_e32 v192, s10
	v_cndmask_b32_e32 v190, v190, v192, vcc
	v_lshlrev_b64 v[188:189], 14, v[188:189]
	v_lshl_add_u64 v[188:189], v[190:191], 0, v[188:189]
	v_lshl_add_u64 v[194:195], v[188:189], 0, v[34:35]
	v_add_co_u32_e32 v188, vcc, s18, v194
	s_nop 1
	v_addc_co_u32_e32 v189, vcc, 0, v195, vcc
	v_add_co_u32_e32 v196, vcc, s19, v194
	global_load_dwordx4 v[22:25], v[188:189], off offset:-4096
	global_load_dwordx4 v[26:29], v[188:189], off
	v_addc_co_u32_e32 v197, vcc, 0, v195, vcc
	global_load_dwordx4 v[30:33], v[194:195], off
	global_load_dwordx4 v[14:17], v[196:197], off
